# v50 + step D: all nine LDS reads issued up front with counted lgkmcnt (removes two serial LDS round trips)
# speedup vs baseline: 1.0104x; 1.0026x over previous
.Lpub_none:
	s_and_saveexec_b64 s[24:25], s[22:23]
	s_cbranch_execz .LBB0_583
	ds_read_b128 v[20:23], v149 offset:56320
	ds_read_b128 v[24:27], v149 offset:56336
	ds_read2st64_b32 v[8:9], v150 offset1:1
	ds_read_b128 v[28:31], v151 offset:9216
	ds_read_b128 v[32:35], v152
	v_add_u32_e32 v87, 0x14800, v106
	ds_read_b128 v[36:39], v87 offset:2304
	ds_read_b128 v[40:43], v87 offset:2320
	ds_read_b128 v[82:85], v87 offset:2560
	ds_read_b128 v[158:161], v87 offset:2576
	s_waitcnt lgkmcnt(6)
	v_add_f32_e32 v11, 0, v20
	v_add_f32_e32 v8, v8, v9
	v_add_f32_e32 v9, v21, v11
	v_add_f32_e32 v9, v22, v9
	v_add_f32_e32 v9, v23, v9
	v_add_f32_e32 v9, v24, v9
	v_add_f32_e32 v9, v25, v9
	v_add_f32_e32 v9, v26, v9
	v_add_f32_e32 v9, v27, v9
	s_waitcnt lgkmcnt(4)
	v_cvt_f32_f16_e32 v164, v28
	v_cvt_f32_f16_sdwa v165, v28 dst_sel:DWORD dst_unused:UNUSED_PAD src0_sel:WORD_1
	v_add_f32_dpp v9, v9, v9 quad_perm:[1,0,3,2] row_mask:0xf bank_mask:0xf bound_ctrl:1
	v_cvt_f32_f16_e32 v28, v29
	v_cvt_f32_f16_sdwa v29, v29 dst_sel:DWORD dst_unused:UNUSED_PAD src0_sel:WORD_1
	v_add_f32_dpp v9, v9, v9 quad_perm:[2,3,0,1] row_mask:0xf bank_mask:0xf bound_ctrl:1
	v_cvt_f32_f16_e32 v166, v32
	v_cvt_f32_f16_sdwa v167, v32 dst_sel:DWORD dst_unused:UNUSED_PAD src0_sel:WORD_1
	v_add_f32_dpp v9, v9, v9 row_half_mirror row_mask:0xf bank_mask:0xf bound_ctrl:1
	v_mul_f32_e32 v86, 0x3c800000, v9
	v_pk_add_f32 v[20:21], v[20:21], v[86:87] op_sel_hi:[1,0] neg_lo:[0,1] neg_hi:[0,1]
	v_pk_mul_f32 v[162:163], v[20:21], v[20:21]
	v_pk_add_f32 v[22:23], v[22:23], v[86:87] op_sel_hi:[1,0] neg_lo:[0,1] neg_hi:[0,1]
	v_pk_mul_f32 v[168:169], v[22:23], v[22:23]
	v_add_f32_e32 v9, v162, v163
	v_pk_add_f32 v[24:25], v[24:25], v[86:87] op_sel_hi:[1,0] neg_lo:[0,1] neg_hi:[0,1]
	v_add_f32_e32 v9, v168, v9
	v_pk_mul_f32 v[170:171], v[24:25], v[24:25]
	v_add_f32_e32 v9, v169, v9
	v_pk_add_f32 v[26:27], v[26:27], v[86:87] op_sel_hi:[1,0] neg_lo:[0,1] neg_hi:[0,1]
	v_add_f32_e32 v9, v170, v9
	v_pk_mul_f32 v[86:87], v[26:27], v[26:27]
	v_add_f32_e32 v9, v171, v9
	v_add_f32_e32 v9, v86, v9
	v_add_f32_e32 v9, v87, v9
	v_cvt_f32_f16_e32 v32, v33
	v_cvt_f32_f16_sdwa v33, v33 dst_sel:DWORD dst_unused:UNUSED_PAD src0_sel:WORD_1
	v_add_f32_dpp v9, v9, v9 quad_perm:[1,0,3,2] row_mask:0xf bank_mask:0xf bound_ctrl:1
	v_cvt_f32_f16_e32 v172, v30
	v_cvt_f32_f16_sdwa v173, v30 dst_sel:DWORD dst_unused:UNUSED_PAD src0_sel:WORD_1
	v_add_f32_dpp v9, v9, v9 quad_perm:[2,3,0,1] row_mask:0xf bank_mask:0xf bound_ctrl:1
	v_cvt_f32_f16_e32 v162, v34
	v_cvt_f32_f16_sdwa v163, v34 dst_sel:DWORD dst_unused:UNUSED_PAD src0_sel:WORD_1
	v_add_f32_dpp v9, v9, v9 row_half_mirror row_mask:0xf bank_mask:0xf bound_ctrl:1
	v_fmamk_f32 v9, v9, 0x3c800000, v153
	v_rsq_f32_e32 v86, v9
	s_nop 0
	v_pk_mul_f32 v[20:21], v[20:21], v[86:87] op_sel_hi:[1,0]
	v_pk_mul_f32 v[22:23], v[22:23], v[86:87] op_sel_hi:[1,0]
	s_waitcnt lgkmcnt(0)
	v_pk_fma_f32 v[20:21], v[36:37], v[20:21], v[82:83]
	v_pk_fma_f32 v[22:23], v[38:39], v[22:23], v[84:85]
	v_pk_fma_f32 v[20:21], v[8:9], v[164:165], v[20:21] op_sel_hi:[0,1,1]
	v_pk_fma_f32 v[22:23], v[8:9], v[28:29], v[22:23] op_sel_hi:[0,1,1]
	v_pk_mul_f32 v[20:21], v[20:21], v[166:167]
	v_pk_mul_f32 v[22:23], v[22:23], v[32:33]
	v_cvt_pk_f16_f32 v20, v20, v21
	v_cvt_pk_f16_f32 v21, v22, v23
	v_pk_mul_f32 v[22:23], v[24:25], v[86:87] op_sel_hi:[1,0]
	v_cvt_f32_f16_e32 v24, v31
	v_cvt_f32_f16_sdwa v25, v31 dst_sel:DWORD dst_unused:UNUSED_PAD src0_sel:WORD_1
	v_cvt_f32_f16_e32 v28, v35
	v_cvt_f32_f16_sdwa v29, v35 dst_sel:DWORD dst_unused:UNUSED_PAD src0_sel:WORD_1
	v_pk_mul_f32 v[26:27], v[26:27], v[86:87] op_sel_hi:[1,0]
	v_pk_fma_f32 v[22:23], v[40:41], v[22:23], v[158:159]
	v_pk_fma_f32 v[26:27], v[42:43], v[26:27], v[160:161]
	v_pk_fma_f32 v[22:23], v[8:9], v[172:173], v[22:23] op_sel_hi:[0,1,1]
	v_pk_fma_f32 v[8:9], v[8:9], v[24:25], v[26:27] op_sel_hi:[0,1,1]
	v_pk_mul_f32 v[22:23], v[22:23], v[162:163]
	v_pk_mul_f32 v[8:9], v[8:9], v[28:29]
	v_cvt_pk_f16_f32 v22, v22, v23
	v_cvt_pk_f16_f32 v23, v8, v9
	v_add_u32_e32 v8, s29, v107
	v_ashrrev_i32_e32 v9, 31, v8
	v_lshlrev_b64 v[8:9], 11, v[8:9]
	v_lshl_add_u64 v[8:9], v[60:61], 0, v[8:9]
	global_store_dwordx4 v[8:9], v[20:23], off sc1
	s_nop 1

.Lds_early:
	s_and_b64 vcc, exec, s[36:37]
	s_cbranch_vccnz .LBB0_581
	s_barrier
	s_and_saveexec_b64 s[24:25], s[22:23]
	s_cbranch_execz .Lds_e583
	ds_read_b128 v[20:23], v149 offset:56320
	ds_read_b128 v[24:27], v149 offset:56336
	ds_read2st64_b32 v[8:9], v150 offset1:1
	ds_read_b128 v[28:31], v151 offset:9216
	ds_read_b128 v[32:35], v152
	v_add_u32_e32 v87, 0x14800, v106
	ds_read_b128 v[36:39], v87 offset:2304
	ds_read_b128 v[40:43], v87 offset:2320
	ds_read_b128 v[82:85], v87 offset:2560
	ds_read_b128 v[158:161], v87 offset:2576
	s_waitcnt lgkmcnt(6)
	v_add_f32_e32 v11, 0, v20
	v_add_f32_e32 v8, v8, v9
	v_add_f32_e32 v9, v21, v11
	v_add_f32_e32 v9, v22, v9
	v_add_f32_e32 v9, v23, v9
	v_add_f32_e32 v9, v24, v9
	v_add_f32_e32 v9, v25, v9
	v_add_f32_e32 v9, v26, v9
	v_add_f32_e32 v9, v27, v9
	s_waitcnt lgkmcnt(4)
	v_cvt_f32_f16_e32 v164, v28
	v_cvt_f32_f16_sdwa v165, v28 dst_sel:DWORD dst_unused:UNUSED_PAD src0_sel:WORD_1
	v_add_f32_dpp v9, v9, v9 quad_perm:[1,0,3,2] row_mask:0xf bank_mask:0xf bound_ctrl:1
	v_cvt_f32_f16_e32 v28, v29
	v_cvt_f32_f16_sdwa v29, v29 dst_sel:DWORD dst_unused:UNUSED_PAD src0_sel:WORD_1
	v_add_f32_dpp v9, v9, v9 quad_perm:[2,3,0,1] row_mask:0xf bank_mask:0xf bound_ctrl:1
	v_cvt_f32_f16_e32 v166, v32
	v_cvt_f32_f16_sdwa v167, v32 dst_sel:DWORD dst_unused:UNUSED_PAD src0_sel:WORD_1
	v_add_f32_dpp v9, v9, v9 row_half_mirror row_mask:0xf bank_mask:0xf bound_ctrl:1
	v_mul_f32_e32 v86, 0x3c800000, v9
	v_pk_add_f32 v[20:21], v[20:21], v[86:87] op_sel_hi:[1,0] neg_lo:[0,1] neg_hi:[0,1]
	v_pk_mul_f32 v[162:163], v[20:21], v[20:21]
	v_pk_add_f32 v[22:23], v[22:23], v[86:87] op_sel_hi:[1,0] neg_lo:[0,1] neg_hi:[0,1]
	v_pk_mul_f32 v[168:169], v[22:23], v[22:23]
	v_add_f32_e32 v9, v162, v163
	v_pk_add_f32 v[24:25], v[24:25], v[86:87] op_sel_hi:[1,0] neg_lo:[0,1] neg_hi:[0,1]
	v_add_f32_e32 v9, v168, v9
	v_pk_mul_f32 v[170:171], v[24:25], v[24:25]
	v_add_f32_e32 v9, v169, v9
	v_pk_add_f32 v[26:27], v[26:27], v[86:87] op_sel_hi:[1,0] neg_lo:[0,1] neg_hi:[0,1]
	v_add_f32_e32 v9, v170, v9
	v_pk_mul_f32 v[86:87], v[26:27], v[26:27]
	v_add_f32_e32 v9, v171, v9
	v_add_f32_e32 v9, v86, v9
	v_add_f32_e32 v9, v87, v9
	v_cvt_f32_f16_e32 v32, v33
	v_cvt_f32_f16_sdwa v33, v33 dst_sel:DWORD dst_unused:UNUSED_PAD src0_sel:WORD_1
	v_add_f32_dpp v9, v9, v9 quad_perm:[1,0,3,2] row_mask:0xf bank_mask:0xf bound_ctrl:1
	v_cvt_f32_f16_e32 v172, v30
	v_cvt_f32_f16_sdwa v173, v30 dst_sel:DWORD dst_unused:UNUSED_PAD src0_sel:WORD_1
	v_add_f32_dpp v9, v9, v9 quad_perm:[2,3,0,1] row_mask:0xf bank_mask:0xf bound_ctrl:1
	v_cvt_f32_f16_e32 v162, v34
	v_cvt_f32_f16_sdwa v163, v34 dst_sel:DWORD dst_unused:UNUSED_PAD src0_sel:WORD_1
	v_add_f32_dpp v9, v9, v9 row_half_mirror row_mask:0xf bank_mask:0xf bound_ctrl:1
	v_fmamk_f32 v9, v9, 0x3c800000, v153
	v_rsq_f32_e32 v86, v9
	s_nop 0
	v_pk_mul_f32 v[20:21], v[20:21], v[86:87] op_sel_hi:[1,0]
	v_pk_mul_f32 v[22:23], v[22:23], v[86:87] op_sel_hi:[1,0]
	s_waitcnt lgkmcnt(0)
	v_pk_fma_f32 v[20:21], v[36:37], v[20:21], v[82:83]
	v_pk_fma_f32 v[22:23], v[38:39], v[22:23], v[84:85]
	v_pk_fma_f32 v[20:21], v[8:9], v[164:165], v[20:21] op_sel_hi:[0,1,1]
	v_pk_fma_f32 v[22:23], v[8:9], v[28:29], v[22:23] op_sel_hi:[0,1,1]
	v_pk_mul_f32 v[20:21], v[20:21], v[166:167]
	v_pk_mul_f32 v[22:23], v[22:23], v[32:33]
	v_cvt_pk_f16_f32 v20, v20, v21
	v_cvt_pk_f16_f32 v21, v22, v23
	v_pk_mul_f32 v[22:23], v[24:25], v[86:87] op_sel_hi:[1,0]
	v_cvt_f32_f16_e32 v24, v31
	v_cvt_f32_f16_sdwa v25, v31 dst_sel:DWORD dst_unused:UNUSED_PAD src0_sel:WORD_1
	v_cvt_f32_f16_e32 v28, v35
	v_cvt_f32_f16_sdwa v29, v35 dst_sel:DWORD dst_unused:UNUSED_PAD src0_sel:WORD_1
	v_pk_mul_f32 v[26:27], v[26:27], v[86:87] op_sel_hi:[1,0]
	v_pk_fma_f32 v[22:23], v[40:41], v[22:23], v[158:159]
	v_pk_fma_f32 v[26:27], v[42:43], v[26:27], v[160:161]
	v_pk_fma_f32 v[22:23], v[8:9], v[172:173], v[22:23] op_sel_hi:[0,1,1]
	v_pk_fma_f32 v[8:9], v[8:9], v[24:25], v[26:27] op_sel_hi:[0,1,1]
	v_pk_mul_f32 v[22:23], v[22:23], v[162:163]
	v_pk_mul_f32 v[8:9], v[8:9], v[28:29]
	v_cvt_pk_f16_f32 v22, v22, v23
	v_cvt_pk_f16_f32 v23, v8, v9
	v_add_u32_e32 v8, s29, v107
	v_ashrrev_i32_e32 v9, 31, v8
	v_lshlrev_b64 v[8:9], 11, v[8:9]
	v_lshl_add_u64 v[8:9], v[60:61], 0, v[8:9]
	global_store_dwordx4 v[8:9], v[20:23], off sc1
	s_nop 1
